# per-section priority toggling also in the phase-9 SUMSQ GEMM loops
# speedup vs baseline: 1.0072x; 1.0021x over previous
.LBB0_69:
	s_add_i32 s3, s0, 1
	s_bitcmp1_b32 s3, 0
	s_cselect_b32 s1, 0x6000, 0
	v_or_b32_e32 v248, s1, v186
	v_add_u32_e32 v237, s1, v205
	v_add_u32_e32 v244, v248, v202
	v_add_u32_e32 v218, v237, v202
	ds_read_b128 v[238:241], v244 offset:16384
	ds_read_b128 v[244:247], v244 offset:18432
	ds_read_b128 v[206:209], v218
	ds_read_b128 v[210:213], v218 offset:2048
	ds_read_b128 v[214:217], v218 offset:4096
	ds_read_b128 v[218:221], v218 offset:6144
	v_mfma_f32_32x32x16_bf16 v[112:127], v[136:139], v[148:151], v[112:127]
	v_mfma_f32_32x32x16_bf16 v[96:111], v[132:135], v[148:151], v[96:111]
	v_mfma_f32_32x32x16_bf16 v[80:95], v[136:139], v[144:147], v[80:95]
	v_mfma_f32_32x32x16_bf16 v[64:79], v[132:135], v[144:147], v[64:79]
	v_mfma_f32_32x32x16_bf16 v[48:63], v[136:139], v[140:143], v[48:63]
	v_mfma_f32_32x32x16_bf16 v[32:47], v[132:135], v[140:143], v[32:47]
	v_mfma_f32_32x32x16_bf16 v[16:31], v[136:139], v[128:131], v[16:31]
	v_add_u32_e32 v136, v237, v204
	v_mfma_f32_32x32x16_bf16 v[0:15], v[132:135], v[128:131], v[0:15]
	v_add_u32_e32 v132, v248, v204
	ds_read_b128 v[148:151], v136
	ds_read_b128 v[144:147], v136 offset:2048
	ds_read_b128 v[140:143], v136 offset:4096
	ds_read_b128 v[128:131], v136 offset:6144
	ds_read_b128 v[136:139], v132 offset:16384
	ds_read_b128 v[132:135], v132 offset:18432
	s_waitcnt lgkmcnt(9)
	v_mfma_f32_32x32x16_bf16 v[112:127], v[238:241], v[206:209], v[112:127]
	v_mfma_f32_32x32x16_bf16 v[96:111], v[244:247], v[206:209], v[96:111]
	s_waitcnt lgkmcnt(8)
	v_mfma_f32_32x32x16_bf16 v[80:95], v[238:241], v[210:213], v[80:95]
	v_mfma_f32_32x32x16_bf16 v[64:79], v[244:247], v[210:213], v[64:79]
	s_waitcnt lgkmcnt(7)
	v_mfma_f32_32x32x16_bf16 v[48:63], v[238:241], v[214:217], v[48:63]
	v_mfma_f32_32x32x16_bf16 v[32:47], v[244:247], v[214:217], v[32:47]
	s_waitcnt lgkmcnt(6)
	v_mfma_f32_32x32x16_bf16 v[16:31], v[238:241], v[218:221], v[16:31]
	v_mfma_f32_32x32x16_bf16 v[0:15], v[244:247], v[218:221], v[0:15]
	s_getreg_b32 s39, hwreg(HW_REG_HW_ID, 0, 4)
	s_bitcmp1_b32 s39, 0
	s_cbranch_scc1 .Lgp100
	s_setprio 0
.Lgp100:
	s_waitcnt vmcnt(5)
	v_dot2c_f32_bf16_e32 v197, v152, v152
	v_dot2c_f32_bf16_e32 v197, v153, v153
	v_dot2c_f32_bf16_e32 v197, v154, v154
	v_dot2c_f32_bf16_e32 v197, v155, v155
	s_waitcnt vmcnt(4)
	v_dot2c_f32_bf16_e32 v196, v156, v156
	v_dot2c_f32_bf16_e32 v196, v157, v157
	v_dot2c_f32_bf16_e32 v196, v158, v158
	v_dot2c_f32_bf16_e32 v196, v159, v159
	s_bitcmp1_b32 s0, 0
	s_cselect_b32 s1, 0x6000, 0
	v_add_u32_e32 v212, s1, v203
	s_waitcnt vmcnt(1)
	ds_write_b128 v212, v[168:171] offset:16384
	v_dot2c_f32_bf16_e32 v199, v160, v160
	v_dot2c_f32_bf16_e32 v199, v161, v161
	v_dot2c_f32_bf16_e32 v199, v162, v162
	v_dot2c_f32_bf16_e32 v199, v163, v163
	v_dot2c_f32_bf16_e32 v198, v164, v164
	v_dot2c_f32_bf16_e32 v198, v165, v165
	v_dot2c_f32_bf16_e32 v198, v166, v166
	v_dot2c_f32_bf16_e32 v198, v167, v167
	s_waitcnt vmcnt(0)
	ds_write_b128 v212, v[172:175] offset:20480
	s_min_u32 s0, s0, 12
	s_lshl_b32 s66, s0, 6
	v_lshl_add_u64 v[168:169], v[176:177], 0, s[66:67]
	s_add_i32 s0, s66, 0xc0
	s_mov_b32 s1, s67
	ds_write_b128 v212, v[152:155]
	global_load_dwordx4 v[152:155], v[168:169], off offset:192
	v_lshl_add_u64 v[168:169], v[180:181], 0, s[0:1]
	ds_write_b128 v212, v[156:159] offset:4096
	global_load_dwordx4 v[156:159], v[168:169], off
	v_lshl_add_u64 v[168:169], v[182:183], 0, s[0:1]
	ds_write_b128 v212, v[160:163] offset:8192
	global_load_dwordx4 v[160:163], v[168:169], off
	v_lshl_add_u64 v[168:169], v[192:193], 0, s[0:1]
	ds_write_b128 v212, v[164:167] offset:12288
	global_load_dwordx4 v[164:167], v[168:169], off
	v_lshl_add_u64 v[168:169], v[178:179], 0, s[66:67]
	v_lshl_add_u64 v[172:173], v[194:195], 0, s[0:1]
	global_load_dwordx4 v[168:171], v[168:169], off offset:192
	s_cmp_eq_u32 s3, 14
	global_load_dwordx4 v[172:175], v[172:173], off
	s_mov_b32 s0, s3
	s_waitcnt lgkmcnt(0)
	s_barrier
	s_setprio 1
	s_cbranch_scc0 .LBB0_69
	s_waitcnt vmcnt(0)
	v_add_u32_e32 v172, v186, v202
	v_add_u32_e32 v164, v205, v202
	ds_read_b128 v[168:171], v172 offset:40960
	ds_read_b128 v[172:175], v172 offset:43008
	ds_read_b128 v[152:155], v164 offset:24576
	ds_read_b128 v[156:159], v164 offset:26624
	ds_read_b128 v[160:163], v164 offset:28672
	ds_read_b128 v[164:167], v164 offset:30720
	v_mfma_f32_32x32x16_bf16 v[112:127], v[136:139], v[148:151], v[112:127]
	v_mfma_f32_32x32x16_bf16 v[96:111], v[132:135], v[148:151], v[96:111]
	v_add_u32_e32 v148, v186, v204
	v_mfma_f32_32x32x16_bf16 v[80:95], v[136:139], v[144:147], v[80:95]
	v_mfma_f32_32x32x16_bf16 v[64:79], v[132:135], v[144:147], v[64:79]
	v_mfma_f32_32x32x16_bf16 v[48:63], v[136:139], v[140:143], v[48:63]
	v_mfma_f32_32x32x16_bf16 v[32:47], v[132:135], v[140:143], v[32:47]
	v_add_u32_e32 v140, v205, v204
	v_mfma_f32_32x32x16_bf16 v[16:31], v[136:139], v[128:131], v[16:31]
	v_mfma_f32_32x32x16_bf16 v[0:15], v[132:135], v[128:131], v[0:15]
	ds_read_b128 v[128:131], v140 offset:24576
	ds_read_b128 v[132:135], v140 offset:26624
	ds_read_b128 v[136:139], v140 offset:28672
	ds_read_b128 v[140:143], v140 offset:30720
	ds_read_b128 v[144:147], v148 offset:40960
	ds_read_b128 v[148:151], v148 offset:43008
	s_waitcnt lgkmcnt(9)
	v_mfma_f32_32x32x16_bf16 v[112:127], v[168:171], v[152:155], v[112:127]
	v_mfma_f32_32x32x16_bf16 v[96:111], v[172:175], v[152:155], v[96:111]
	s_waitcnt lgkmcnt(8)
	v_mfma_f32_32x32x16_bf16 v[80:95], v[168:171], v[156:159], v[80:95]
	v_mfma_f32_32x32x16_bf16 v[64:79], v[172:175], v[156:159], v[64:79]
	s_waitcnt lgkmcnt(7)
	v_mfma_f32_32x32x16_bf16 v[48:63], v[168:171], v[160:163], v[48:63]
	v_mfma_f32_32x32x16_bf16 v[32:47], v[172:175], v[160:163], v[32:47]
	s_waitcnt lgkmcnt(6)
	v_mfma_f32_32x32x16_bf16 v[16:31], v[168:171], v[164:167], v[16:31]
	v_mfma_f32_32x32x16_bf16 v[0:15], v[172:175], v[164:167], v[0:15]
	v_cmp_lt_i32_e32 vcc, v233, v227
	s_waitcnt lgkmcnt(1)
	v_mfma_f32_32x32x16_bf16 v[112:127], v[144:147], v[128:131], v[112:127]
	s_waitcnt lgkmcnt(0)
	s_barrier
	v_mfma_f32_32x32x16_bf16 v[96:111], v[148:151], v[128:131], v[96:111]
	v_cndmask_b32_e32 v128, v226, v233, vcc
	v_lshlrev_b32_e32 v130, 2, v128
	ds_bpermute_b32 v129, v130, v197
	ds_bpermute_b32 v128, v130, v196
	ds_bpermute_b32 v131, v130, v199
	ds_bpermute_b32 v130, v130, v198
	v_cmp_lt_i32_e32 vcc, v232, v227
	v_mfma_f32_32x32x16_bf16 v[80:95], v[144:147], v[132:135], v[80:95]
	v_mfma_f32_32x32x16_bf16 v[64:79], v[148:151], v[132:135], v[64:79]
	s_waitcnt lgkmcnt(2)
	v_add_f32_e64 v132, v196, v128
	v_add_f32_e64 v133, v197, v129
	s_waitcnt lgkmcnt(0)
	v_add_f32_e64 v128, v198, v130
	v_add_f32_e64 v129, v199, v131
	v_cndmask_b32_e32 v130, v226, v232, vcc
	v_lshlrev_b32_e32 v130, 2, v130
	ds_bpermute_b32 v135, v130, v133
	ds_bpermute_b32 v134, v130, v132
	ds_bpermute_b32 v131, v130, v129
	v_mfma_f32_32x32x16_bf16 v[48:63], v[144:147], v[136:139], v[48:63]
	ds_bpermute_b32 v130, v130, v128
	v_cmp_eq_u32_e32 vcc, 0, v201
	v_mfma_f32_32x32x16_bf16 v[32:47], v[148:151], v[136:139], v[32:47]
	v_mfma_f32_32x32x16_bf16 v[16:31], v[144:147], v[140:143], v[16:31]
	v_mfma_f32_32x32x16_bf16 v[0:15], v[148:151], v[140:143], v[0:15]
	s_and_saveexec_b64 s[0:1], vcc
	s_cbranch_execz .LBB0_72
	s_mov_b32 s10, 0x358637bd
	s_waitcnt lgkmcnt(2)
	v_pk_add_f32 v[132:133], v[132:133], v[134:135]
	v_mov_b64_e32 v[134:135], s[10:11]
	s_mov_b32 s26, 0x3b000000
	v_pk_fma_f32 v[132:133], v[132:133], s[26:27], v[134:135] op_sel_hi:[1,0,0]
	s_waitcnt lgkmcnt(0)
	v_pk_add_f32 v[128:129], v[128:129], v[130:131]
	v_mul_f32_e32 v136, 0x4b800000, v133
	v_cmp_gt_f32_e32 vcc, s80, v133
	v_cmp_gt_f32_e64 s[10:11], s80, v132
	v_pk_fma_f32 v[128:129], v[128:129], s[26:27], v[134:135] op_sel_hi:[1,0,0]
	v_cndmask_b32_e32 v133, v133, v136, vcc
	v_mul_f32_e32 v136, 0x4b800000, v132
	v_rsq_f32_e32 v133, v133
	v_cndmask_b32_e64 v132, v132, v136, s[10:11]
	v_rsq_f32_e32 v132, v132
	v_mul_f32_e32 v130, 0x4b800000, v129
	v_mul_f32_e32 v137, 0x45800000, v133
	v_cndmask_b32_e32 v133, v133, v137, vcc
	v_mul_f32_e32 v137, 0x45800000, v132
	v_cmp_gt_f32_e32 vcc, s80, v129
	v_cndmask_b32_e64 v132, v132, v137, s[10:11]
	v_cmp_gt_f32_e64 s[10:11], s80, v128
	v_cndmask_b32_e32 v129, v129, v130, vcc
	v_mul_f32_e32 v130, 0x4b800000, v128
	v_rsq_f32_e32 v129, v129
	v_cndmask_b32_e64 v128, v128, v130, s[10:11]
	v_rsq_f32_e32 v128, v128
	v_lshlrev_b32_e32 v136, 2, v200
	v_mul_f32_e32 v130, 0x45800000, v129
	v_cndmask_b32_e32 v129, v129, v130, vcc
	v_mul_f32_e32 v130, 0x45800000, v128
	v_cndmask_b32_e64 v128, v128, v130, s[10:11]
	ds_write2st64_b32 v136, v133, v132 offset0:192 offset1:193
	ds_write2st64_b32 v136, v129, v128 offset0:194 offset1:195

.LBB0_75:
	s_add_i32 s3, s0, 1
	s_bitcmp1_b32 s3, 0
	s_cselect_b32 s1, 0x6000, 0
	v_add_u32_e32 v237, s1, v186
	v_or_b32_e32 v248, s1, v204
	v_add_u32_e32 v218, v237, v202
	v_add_u32_e32 v244, v248, v202
	ds_read_b128 v[206:209], v218
	ds_read_b128 v[210:213], v218 offset:2048
	ds_read_b128 v[214:217], v218 offset:4096
	ds_read_b128 v[218:221], v218 offset:6144
	ds_read_b128 v[238:241], v244 offset:16384
	ds_read_b128 v[244:247], v244 offset:18432
	v_mfma_f32_32x32x16_bf16 v[112:127], v[148:151], v[136:139], v[112:127]
	v_mfma_f32_32x32x16_bf16 v[96:111], v[148:151], v[132:135], v[96:111]
	v_mfma_f32_32x32x16_bf16 v[80:95], v[144:147], v[136:139], v[80:95]
	v_mfma_f32_32x32x16_bf16 v[64:79], v[144:147], v[132:135], v[64:79]
	v_mfma_f32_32x32x16_bf16 v[48:63], v[140:143], v[136:139], v[48:63]
	v_mfma_f32_32x32x16_bf16 v[32:47], v[140:143], v[132:135], v[32:47]
	v_mfma_f32_32x32x16_bf16 v[16:31], v[128:131], v[136:139], v[16:31]
	v_add_u32_e32 v136, v237, v205
	v_mfma_f32_32x32x16_bf16 v[0:15], v[128:131], v[132:135], v[0:15]
	v_add_u32_e32 v132, v248, v205
	ds_read_b128 v[148:151], v136
	ds_read_b128 v[144:147], v136 offset:2048
	ds_read_b128 v[140:143], v136 offset:4096
	ds_read_b128 v[128:131], v136 offset:6144
	ds_read_b128 v[136:139], v132 offset:16384
	ds_read_b128 v[132:135], v132 offset:18432
	s_waitcnt lgkmcnt(7)
	v_mfma_f32_32x32x16_bf16 v[112:127], v[206:209], v[238:241], v[112:127]
	s_waitcnt lgkmcnt(6)
	v_mfma_f32_32x32x16_bf16 v[96:111], v[206:209], v[244:247], v[96:111]
	v_mfma_f32_32x32x16_bf16 v[80:95], v[210:213], v[238:241], v[80:95]
	v_mfma_f32_32x32x16_bf16 v[64:79], v[210:213], v[244:247], v[64:79]
	v_mfma_f32_32x32x16_bf16 v[48:63], v[214:217], v[238:241], v[48:63]
	v_mfma_f32_32x32x16_bf16 v[32:47], v[214:217], v[244:247], v[32:47]
	v_mfma_f32_32x32x16_bf16 v[16:31], v[218:221], v[238:241], v[16:31]
	v_mfma_f32_32x32x16_bf16 v[0:15], v[218:221], v[244:247], v[0:15]
	s_getreg_b32 s39, hwreg(HW_REG_HW_ID, 0, 4)
	s_bitcmp1_b32 s39, 0
	s_cbranch_scc1 .Lgp101
	s_setprio 0
.Lgp101:
	s_waitcnt vmcnt(5)
	v_dot2c_f32_bf16_e32 v197, v152, v152
	v_dot2c_f32_bf16_e32 v197, v153, v153
	v_dot2c_f32_bf16_e32 v197, v154, v154
	v_dot2c_f32_bf16_e32 v197, v155, v155
	s_waitcnt vmcnt(4)
	v_dot2c_f32_bf16_e32 v196, v156, v156
	v_dot2c_f32_bf16_e32 v196, v157, v157
	v_dot2c_f32_bf16_e32 v196, v158, v158
	v_dot2c_f32_bf16_e32 v196, v159, v159
	s_bitcmp1_b32 s0, 0
	s_cselect_b32 s1, 0x6000, 0
	v_add_u32_e32 v212, s1, v203
	s_waitcnt vmcnt(1)
	ds_write_b128 v212, v[168:171] offset:16384
	v_dot2c_f32_bf16_e32 v199, v160, v160
	v_dot2c_f32_bf16_e32 v199, v161, v161
	v_dot2c_f32_bf16_e32 v199, v162, v162
	v_dot2c_f32_bf16_e32 v199, v163, v163
	v_dot2c_f32_bf16_e32 v198, v164, v164
	v_dot2c_f32_bf16_e32 v198, v165, v165
	v_dot2c_f32_bf16_e32 v198, v166, v166
	v_dot2c_f32_bf16_e32 v198, v167, v167
	s_waitcnt vmcnt(0)
	ds_write_b128 v212, v[172:175] offset:20480
	s_min_u32 s0, s0, 12
	s_lshl_b32 s66, s0, 6
	v_lshl_add_u64 v[168:169], v[176:177], 0, s[66:67]
	s_add_i32 s0, s66, 0xc0
	s_mov_b32 s1, s67
	ds_write_b128 v212, v[152:155]
	global_load_dwordx4 v[152:155], v[168:169], off offset:192
	v_lshl_add_u64 v[168:169], v[180:181], 0, s[0:1]
	ds_write_b128 v212, v[156:159] offset:4096
	global_load_dwordx4 v[156:159], v[168:169], off
	v_lshl_add_u64 v[168:169], v[182:183], 0, s[0:1]
	ds_write_b128 v212, v[160:163] offset:8192
	global_load_dwordx4 v[160:163], v[168:169], off
	v_lshl_add_u64 v[168:169], v[192:193], 0, s[0:1]
	ds_write_b128 v212, v[164:167] offset:12288
	global_load_dwordx4 v[164:167], v[168:169], off
	v_lshl_add_u64 v[168:169], v[178:179], 0, s[66:67]
	v_lshl_add_u64 v[172:173], v[194:195], 0, s[0:1]
	global_load_dwordx4 v[168:171], v[168:169], off offset:192
	s_cmp_eq_u32 s3, 14
	global_load_dwordx4 v[172:175], v[172:173], off
	s_mov_b32 s0, s3
	s_waitcnt lgkmcnt(0)
	s_barrier
	s_setprio 1
	s_cbranch_scc0 .LBB0_75
	s_waitcnt vmcnt(2)
	v_add_u32_e32 v164, v186, v202
	ds_read_b128 v[152:155], v164 offset:24576
	ds_read_b128 v[156:159], v164 offset:26624
	ds_read_b128 v[160:163], v164 offset:28672
	ds_read_b128 v[164:167], v164 offset:30720
	s_waitcnt vmcnt(0)
	v_add_u32_e32 v172, v204, v202
	ds_read_b128 v[168:171], v172 offset:40960
	ds_read_b128 v[172:175], v172 offset:43008
	v_mfma_f32_32x32x16_bf16 v[112:127], v[148:151], v[136:139], v[112:127]
	v_mfma_f32_32x32x16_bf16 v[96:111], v[148:151], v[132:135], v[96:111]
	v_add_u32_e32 v148, v204, v205
	v_mfma_f32_32x32x16_bf16 v[80:95], v[144:147], v[136:139], v[80:95]
	v_mfma_f32_32x32x16_bf16 v[64:79], v[144:147], v[132:135], v[64:79]
	v_mfma_f32_32x32x16_bf16 v[48:63], v[140:143], v[136:139], v[48:63]
	v_mfma_f32_32x32x16_bf16 v[32:47], v[140:143], v[132:135], v[32:47]
	v_add_u32_e32 v140, v186, v205
	v_mfma_f32_32x32x16_bf16 v[16:31], v[128:131], v[136:139], v[16:31]
	v_mfma_f32_32x32x16_bf16 v[0:15], v[128:131], v[132:135], v[0:15]
	ds_read_b128 v[128:131], v140 offset:24576
	ds_read_b128 v[132:135], v140 offset:26624
	ds_read_b128 v[136:139], v140 offset:28672
	ds_read_b128 v[140:143], v140 offset:30720
	ds_read_b128 v[144:147], v148 offset:40960
	ds_read_b128 v[148:151], v148 offset:43008
	s_waitcnt lgkmcnt(7)
	v_mfma_f32_32x32x16_bf16 v[112:127], v[152:155], v[168:171], v[112:127]
	s_waitcnt lgkmcnt(6)
	v_mfma_f32_32x32x16_bf16 v[96:111], v[152:155], v[172:175], v[96:111]
	v_mfma_f32_32x32x16_bf16 v[80:95], v[156:159], v[168:171], v[80:95]
	v_mfma_f32_32x32x16_bf16 v[64:79], v[156:159], v[172:175], v[64:79]
	v_mfma_f32_32x32x16_bf16 v[48:63], v[160:163], v[168:171], v[48:63]
	v_mfma_f32_32x32x16_bf16 v[32:47], v[160:163], v[172:175], v[32:47]
	v_mfma_f32_32x32x16_bf16 v[16:31], v[164:167], v[168:171], v[16:31]
	v_mfma_f32_32x32x16_bf16 v[0:15], v[164:167], v[172:175], v[0:15]
	v_cmp_lt_i32_e32 vcc, v233, v227
	s_waitcnt lgkmcnt(1)
	v_mfma_f32_32x32x16_bf16 v[112:127], v[128:131], v[144:147], v[112:127]
	s_waitcnt lgkmcnt(0)
	s_barrier
	v_mfma_f32_32x32x16_bf16 v[96:111], v[128:131], v[148:151], v[96:111]
	v_cndmask_b32_e32 v128, v226, v233, vcc
	v_lshlrev_b32_e32 v130, 2, v128
	ds_bpermute_b32 v129, v130, v197
	ds_bpermute_b32 v128, v130, v196
	ds_bpermute_b32 v131, v130, v199
	ds_bpermute_b32 v130, v130, v198
	v_cmp_lt_i32_e32 vcc, v232, v227
	v_mfma_f32_32x32x16_bf16 v[80:95], v[132:135], v[144:147], v[80:95]
	v_mfma_f32_32x32x16_bf16 v[64:79], v[132:135], v[148:151], v[64:79]
	s_waitcnt lgkmcnt(2)
	v_add_f32_e64 v132, v196, v128
	v_add_f32_e64 v133, v197, v129
	s_waitcnt lgkmcnt(0)
	v_add_f32_e64 v128, v198, v130
	v_add_f32_e64 v129, v199, v131
	v_cndmask_b32_e32 v130, v226, v232, vcc
	v_lshlrev_b32_e32 v130, 2, v130
	ds_bpermute_b32 v135, v130, v133
	ds_bpermute_b32 v134, v130, v132
	ds_bpermute_b32 v131, v130, v129
	v_mfma_f32_32x32x16_bf16 v[48:63], v[136:139], v[144:147], v[48:63]
	ds_bpermute_b32 v130, v130, v128
	v_cmp_eq_u32_e32 vcc, 0, v201
	v_mfma_f32_32x32x16_bf16 v[32:47], v[136:139], v[148:151], v[32:47]
	v_mfma_f32_32x32x16_bf16 v[16:31], v[140:143], v[144:147], v[16:31]
	v_mfma_f32_32x32x16_bf16 v[0:15], v[140:143], v[148:151], v[0:15]
	s_and_saveexec_b64 s[0:1], vcc
	s_cbranch_execz .LBB0_78
	s_mov_b32 s10, 0x358637bd
	s_waitcnt lgkmcnt(2)
	v_pk_add_f32 v[132:133], v[132:133], v[134:135]
	v_mov_b64_e32 v[134:135], s[10:11]
	s_mov_b32 s26, 0x3b000000
	v_pk_fma_f32 v[132:133], v[132:133], s[26:27], v[134:135] op_sel_hi:[1,0,0]
	s_waitcnt lgkmcnt(0)
	v_pk_add_f32 v[128:129], v[128:129], v[130:131]
	v_mul_f32_e32 v136, 0x4b800000, v133
	v_cmp_gt_f32_e32 vcc, s80, v133
	v_cmp_gt_f32_e64 s[10:11], s80, v132
	v_pk_fma_f32 v[128:129], v[128:129], s[26:27], v[134:135] op_sel_hi:[1,0,0]
	v_cndmask_b32_e32 v133, v133, v136, vcc
	v_mul_f32_e32 v136, 0x4b800000, v132
	v_rsq_f32_e32 v133, v133
	v_cndmask_b32_e64 v132, v132, v136, s[10:11]
	v_rsq_f32_e32 v132, v132
	v_mul_f32_e32 v130, 0x4b800000, v129
	v_mul_f32_e32 v137, 0x45800000, v133
	v_cndmask_b32_e32 v133, v133, v137, vcc
	v_mul_f32_e32 v137, 0x45800000, v132
	v_cmp_gt_f32_e32 vcc, s80, v129
	v_cndmask_b32_e64 v132, v132, v137, s[10:11]
	v_cmp_gt_f32_e64 s[10:11], s80, v128
	v_cndmask_b32_e32 v129, v129, v130, vcc
	v_mul_f32_e32 v130, 0x4b800000, v128
	v_rsq_f32_e32 v129, v129
	v_cndmask_b32_e64 v128, v128, v130, s[10:11]
	v_rsq_f32_e32 v128, v128
	v_lshlrev_b32_e32 v136, 2, v200
	v_mul_f32_e32 v130, 0x45800000, v129
	v_cndmask_b32_e32 v129, v129, v130, vcc
	v_mul_f32_e32 v130, 0x45800000, v128
	v_cndmask_b32_e64 v128, v128, v130, s[10:11]
	ds_write2st64_b32 v136, v133, v132 offset0:192 offset1:193
	ds_write2st64_b32 v136, v129, v128 offset0:194 offset1:195

.LBB0_81:
	s_add_i32 s9, s0, 1
	s_bitcmp1_b32 s9, 0
	s_cselect_b32 s1, 0x6000, 0
	v_add_u32_e32 v218, s1, v186
	v_or_b32_e32 v219, s1, v204
	v_add_u32_e32 v220, v218, v202
	v_add_u32_e32 v221, v219, v202
	ds_read_b128 v[206:209], v220
	ds_read_b128 v[210:213], v220 offset:2048
	ds_read_b128 v[214:217], v220 offset:4096
	ds_read_b128 v[238:241], v220 offset:6144
	ds_read_b128 v[244:247], v221 offset:16384
	ds_read_b128 v[248:251], v221 offset:18432
	v_mfma_f32_32x32x16_bf16 v[112:127], v[148:151], v[136:139], v[112:127]
	v_mfma_f32_32x32x16_bf16 v[96:111], v[148:151], v[132:135], v[96:111]
	v_mfma_f32_32x32x16_bf16 v[80:95], v[144:147], v[136:139], v[80:95]
	v_mfma_f32_32x32x16_bf16 v[64:79], v[144:147], v[132:135], v[64:79]
	v_mfma_f32_32x32x16_bf16 v[48:63], v[140:143], v[136:139], v[48:63]
	v_mfma_f32_32x32x16_bf16 v[32:47], v[140:143], v[132:135], v[32:47]
	v_mfma_f32_32x32x16_bf16 v[16:31], v[128:131], v[136:139], v[16:31]
	v_add_u32_e32 v136, v218, v205
	v_mfma_f32_32x32x16_bf16 v[0:15], v[128:131], v[132:135], v[0:15]
	v_add_u32_e32 v132, v219, v205
	ds_read_b128 v[148:151], v136
	ds_read_b128 v[144:147], v136 offset:2048
	ds_read_b128 v[140:143], v136 offset:4096
	ds_read_b128 v[128:131], v136 offset:6144
	ds_read_b128 v[136:139], v132 offset:16384
	ds_read_b128 v[132:135], v132 offset:18432
	s_waitcnt lgkmcnt(7)
	v_mfma_f32_32x32x16_bf16 v[112:127], v[206:209], v[244:247], v[112:127]
	s_waitcnt lgkmcnt(6)
	v_mfma_f32_32x32x16_bf16 v[96:111], v[206:209], v[248:251], v[96:111]
	v_mfma_f32_32x32x16_bf16 v[80:95], v[210:213], v[244:247], v[80:95]
	v_mfma_f32_32x32x16_bf16 v[64:79], v[210:213], v[248:251], v[64:79]
	v_mfma_f32_32x32x16_bf16 v[48:63], v[214:217], v[244:247], v[48:63]
	v_mfma_f32_32x32x16_bf16 v[32:47], v[214:217], v[248:251], v[32:47]
	v_mfma_f32_32x32x16_bf16 v[16:31], v[238:241], v[244:247], v[16:31]
	v_mfma_f32_32x32x16_bf16 v[0:15], v[238:241], v[248:251], v[0:15]
	s_getreg_b32 s39, hwreg(HW_REG_HW_ID, 0, 4)
	s_bitcmp1_b32 s39, 0
	s_cbranch_scc1 .Lgp102
	s_setprio 0
.Lgp102:
	s_waitcnt vmcnt(5)
	v_dot2c_f32_bf16_e32 v197, v152, v152
	v_dot2c_f32_bf16_e32 v197, v153, v153
	v_dot2c_f32_bf16_e32 v197, v154, v154
	v_dot2c_f32_bf16_e32 v197, v155, v155
	s_waitcnt vmcnt(4)
	v_dot2c_f32_bf16_e32 v196, v156, v156
	v_dot2c_f32_bf16_e32 v196, v157, v157
	v_dot2c_f32_bf16_e32 v196, v158, v158
	v_dot2c_f32_bf16_e32 v196, v159, v159
	s_bitcmp1_b32 s0, 0
	s_cselect_b32 s1, 0x6000, 0
	v_add_u32_e32 v212, s1, v203
	s_waitcnt vmcnt(1)
	ds_write_b128 v212, v[168:171] offset:16384
	v_dot2c_f32_bf16_e32 v199, v160, v160
	v_dot2c_f32_bf16_e32 v199, v161, v161
	v_dot2c_f32_bf16_e32 v199, v162, v162
	v_dot2c_f32_bf16_e32 v199, v163, v163
	v_dot2c_f32_bf16_e32 v198, v164, v164
	v_dot2c_f32_bf16_e32 v198, v165, v165
	v_dot2c_f32_bf16_e32 v198, v166, v166
	v_dot2c_f32_bf16_e32 v198, v167, v167
	s_waitcnt vmcnt(0)
	ds_write_b128 v212, v[172:175] offset:20480
	s_min_u32 s0, s0, 12
	s_lshl_b32 s66, s0, 6
	v_lshl_add_u64 v[168:169], v[176:177], 0, s[66:67]
	s_add_i32 s0, s66, 0xc0
	s_mov_b32 s1, s67
	ds_write_b128 v212, v[152:155]
	global_load_dwordx4 v[152:155], v[168:169], off offset:192
	v_lshl_add_u64 v[168:169], v[180:181], 0, s[0:1]
	ds_write_b128 v212, v[156:159] offset:4096
	global_load_dwordx4 v[156:159], v[168:169], off
	v_lshl_add_u64 v[168:169], v[182:183], 0, s[0:1]
	ds_write_b128 v212, v[160:163] offset:8192
	global_load_dwordx4 v[160:163], v[168:169], off
	v_lshl_add_u64 v[168:169], v[192:193], 0, s[0:1]
	ds_write_b128 v212, v[164:167] offset:12288
	global_load_dwordx4 v[164:167], v[168:169], off
	v_lshl_add_u64 v[168:169], v[178:179], 0, s[66:67]
	v_lshl_add_u64 v[172:173], v[194:195], 0, s[0:1]
	global_load_dwordx4 v[168:171], v[168:169], off offset:192
	s_cmp_eq_u32 s9, 14
	global_load_dwordx4 v[172:175], v[172:173], off
	s_mov_b32 s0, s9
	s_waitcnt lgkmcnt(0)
	s_barrier
	s_setprio 1
	s_cbranch_scc0 .LBB0_81
	s_waitcnt vmcnt(2)
	v_add_u32_e32 v164, v186, v202
	ds_read_b128 v[152:155], v164 offset:24576
	ds_read_b128 v[156:159], v164 offset:26624
	ds_read_b128 v[160:163], v164 offset:28672
	ds_read_b128 v[164:167], v164 offset:30720
	s_waitcnt vmcnt(0)
	v_add_u32_e32 v172, v204, v202
	ds_read_b128 v[168:171], v172 offset:40960
	ds_read_b128 v[172:175], v172 offset:43008
	v_mfma_f32_32x32x16_bf16 v[112:127], v[148:151], v[136:139], v[112:127]
	v_mfma_f32_32x32x16_bf16 v[96:111], v[148:151], v[132:135], v[96:111]
	v_add_u32_e32 v148, v204, v205
	v_mfma_f32_32x32x16_bf16 v[80:95], v[144:147], v[136:139], v[80:95]
	v_mfma_f32_32x32x16_bf16 v[64:79], v[144:147], v[132:135], v[64:79]
	v_mfma_f32_32x32x16_bf16 v[48:63], v[140:143], v[136:139], v[48:63]
	v_mfma_f32_32x32x16_bf16 v[32:47], v[140:143], v[132:135], v[32:47]
	v_add_u32_e32 v140, v186, v205
	v_mfma_f32_32x32x16_bf16 v[16:31], v[128:131], v[136:139], v[16:31]
	v_mfma_f32_32x32x16_bf16 v[0:15], v[128:131], v[132:135], v[0:15]
	ds_read_b128 v[128:131], v140 offset:24576
	ds_read_b128 v[132:135], v140 offset:26624
	ds_read_b128 v[136:139], v140 offset:28672
	ds_read_b128 v[140:143], v140 offset:30720
	ds_read_b128 v[144:147], v148 offset:40960
	ds_read_b128 v[148:151], v148 offset:43008
	s_waitcnt lgkmcnt(7)
	v_mfma_f32_32x32x16_bf16 v[112:127], v[152:155], v[168:171], v[112:127]
	s_waitcnt lgkmcnt(6)
	v_mfma_f32_32x32x16_bf16 v[96:111], v[152:155], v[172:175], v[96:111]
	v_mfma_f32_32x32x16_bf16 v[80:95], v[156:159], v[168:171], v[80:95]
	v_mfma_f32_32x32x16_bf16 v[64:79], v[156:159], v[172:175], v[64:79]
	v_mfma_f32_32x32x16_bf16 v[48:63], v[160:163], v[168:171], v[48:63]
	v_mfma_f32_32x32x16_bf16 v[32:47], v[160:163], v[172:175], v[32:47]
	v_mfma_f32_32x32x16_bf16 v[16:31], v[164:167], v[168:171], v[16:31]
	v_mfma_f32_32x32x16_bf16 v[0:15], v[164:167], v[172:175], v[0:15]
	v_cmp_lt_i32_e32 vcc, v233, v227
	s_waitcnt lgkmcnt(1)
	v_mfma_f32_32x32x16_bf16 v[112:127], v[128:131], v[144:147], v[112:127]
	s_waitcnt lgkmcnt(0)
	s_barrier
	v_mfma_f32_32x32x16_bf16 v[96:111], v[128:131], v[148:151], v[96:111]
	v_cndmask_b32_e32 v128, v226, v233, vcc
	v_lshlrev_b32_e32 v130, 2, v128
	ds_bpermute_b32 v129, v130, v197
	ds_bpermute_b32 v128, v130, v196
	ds_bpermute_b32 v131, v130, v199
	ds_bpermute_b32 v130, v130, v198
	v_cmp_lt_i32_e32 vcc, v232, v227
	v_mfma_f32_32x32x16_bf16 v[80:95], v[132:135], v[144:147], v[80:95]
	v_mfma_f32_32x32x16_bf16 v[64:79], v[132:135], v[148:151], v[64:79]
	s_waitcnt lgkmcnt(2)
	v_add_f32_e64 v132, v196, v128
	v_add_f32_e64 v133, v197, v129
	s_waitcnt lgkmcnt(0)
	v_add_f32_e64 v128, v198, v130
	v_add_f32_e64 v129, v199, v131
	v_cndmask_b32_e32 v130, v226, v232, vcc
	v_lshlrev_b32_e32 v130, 2, v130
	ds_bpermute_b32 v135, v130, v133
	ds_bpermute_b32 v134, v130, v132
	ds_bpermute_b32 v131, v130, v129
	v_mfma_f32_32x32x16_bf16 v[48:63], v[136:139], v[144:147], v[48:63]
	ds_bpermute_b32 v130, v130, v128
	v_cmp_eq_u32_e32 vcc, 0, v201
	v_mfma_f32_32x32x16_bf16 v[32:47], v[136:139], v[148:151], v[32:47]
	v_mfma_f32_32x32x16_bf16 v[16:31], v[140:143], v[144:147], v[16:31]
	v_mfma_f32_32x32x16_bf16 v[0:15], v[140:143], v[148:151], v[0:15]
	s_and_saveexec_b64 s[0:1], vcc
	s_cbranch_execz .LBB0_84
	s_mov_b32 s10, 0x358637bd
	s_waitcnt lgkmcnt(2)
	v_pk_add_f32 v[132:133], v[132:133], v[134:135]
	v_mov_b64_e32 v[134:135], s[10:11]
	s_mov_b32 s24, 0x3b000000
	v_pk_fma_f32 v[132:133], v[132:133], s[24:25], v[134:135] op_sel_hi:[1,0,0]
	s_waitcnt lgkmcnt(0)
	v_pk_add_f32 v[128:129], v[128:129], v[130:131]
	v_mul_f32_e32 v136, 0x4b800000, v133
	v_cmp_gt_f32_e32 vcc, s80, v133
	v_cmp_gt_f32_e64 s[10:11], s80, v132
	v_pk_fma_f32 v[128:129], v[128:129], s[24:25], v[134:135] op_sel_hi:[1,0,0]
	v_cndmask_b32_e32 v133, v133, v136, vcc
	v_mul_f32_e32 v136, 0x4b800000, v132
	v_rsq_f32_e32 v133, v133
	v_cndmask_b32_e64 v132, v132, v136, s[10:11]
	v_rsq_f32_e32 v132, v132
	v_mul_f32_e32 v130, 0x4b800000, v129
	v_mul_f32_e32 v137, 0x45800000, v133
	v_cndmask_b32_e32 v133, v133, v137, vcc
	v_mul_f32_e32 v137, 0x45800000, v132
	v_cmp_gt_f32_e32 vcc, s80, v129
	v_cndmask_b32_e64 v132, v132, v137, s[10:11]
	v_cmp_gt_f32_e64 s[10:11], s80, v128
	v_cndmask_b32_e32 v129, v129, v130, vcc
	v_mul_f32_e32 v130, 0x4b800000, v128
	v_rsq_f32_e32 v129, v129
	v_cndmask_b32_e64 v128, v128, v130, s[10:11]
	v_rsq_f32_e32 v128, v128
	v_lshlrev_b32_e32 v136, 2, v200
	v_mul_f32_e32 v130, 0x45800000, v129
	v_cndmask_b32_e32 v129, v129, v130, vcc
	v_mul_f32_e32 v130, 0x45800000, v128
	v_cndmask_b32_e64 v128, v128, v130, s[10:11]
	ds_write2st64_b32 v136, v133, v132 offset0:192 offset1:193
	ds_write2st64_b32 v136, v129, v128 offset0:194 offset1:195
